# in-proj epilogue: Q stores widened to dwordx4 (column-block pairs exchanged between lane pairs with v_permlane16_swap), 2 stores per row group instead of 4
# speedup vs baseline: 1.0335x; 1.0029x over previous
; DI u32x2 pk4(f32x4 v) { u32x2 r; r.x = pk2(v[0], v[1]); r.y = pk2(v[2], v[3]); return r; }
;     DI void operator()(const AccT& acc, const Unit& u, int wr, int wc, int fr, int fq, LAS unsigned char*) const {
;     ...
;                 if (kind == 0 || kind == 3) {
;                     bf16_t* q = (bf16_t*)(ws + (kind == 0 ? WS_QA : WS_QB)) + ((size_t)h * MTOK + row) * 64 + 4 * fq;
; #pragma unroll
;                     for (int bj = 0; bj < 2; ++bj)
; #pragma unroll
;                         for (int n = 0; n < 2; ++n) *(u32x2*)(q + 32 * bj + 16 * n) = pk4(v[bj][n] * QSCALE);
.LBB0_181:
	s_mul_hi_i32 s55, s44, 0x4800
	s_mul_i32 s54, s44, 0x4800
	s_and_b64 vcc, exec, s[10:11]
	s_cbranch_vccz .LBB0_179
	v_ashrrev_i32_e32 v183, 31, v182
	s_add_u32 s10, s36, s29
	v_lshl_add_u64 v[184:185], s[54:55], 0, v[182:183]
	s_addc_u32 s11, s37, 0
	v_lshlrev_b64 v[184:185], 7, v[184:185]
	v_lshl_add_u64 v[184:185], s[10:11], 0, v[184:185]
	v_lshlrev_b32_e32 v150, 1, v152
	v_pk_mul_f32 v[142:143], v[142:143], s[26:27] op_sel_hi:[1,0]
	v_pk_mul_f32 v[140:141], v[140:141], s[26:27] op_sel_hi:[1,0]
	v_pk_mul_f32 v[138:139], v[138:139], s[26:27] op_sel_hi:[1,0]
	v_pk_mul_f32 v[136:137], v[136:137], s[26:27] op_sel_hi:[1,0]
	v_pk_mul_f32 v[134:135], v[134:135], s[26:27] op_sel_hi:[1,0]
	v_pk_mul_f32 v[132:133], v[132:133], s[26:27] op_sel_hi:[1,0]
	v_pk_mul_f32 v[130:131], v[130:131], s[26:27] op_sel_hi:[1,0]
	v_pk_mul_f32 v[128:129], v[128:129], s[26:27] op_sel_hi:[1,0]
	v_lshl_add_u64 v[184:185], v[184:185], 0, v[150:151]
	v_and_b32_e32 v150, 8, v150
	v_mul_u32_u24_e32 v150, 3, v150
	v_lshl_add_u64 v[184:185], v[184:185], 0, v[150:151]
	v_cvt_pk_bf16_f32 v140, v140, v141
	v_cvt_pk_bf16_f32 v141, v142, v143
	v_cvt_pk_bf16_f32 v142, v136, v137
	v_cvt_pk_bf16_f32 v143, v138, v139
	v_cvt_pk_bf16_f32 v132, v132, v133
	v_cvt_pk_bf16_f32 v133, v134, v135
	v_cvt_pk_bf16_f32 v134, v128, v129
	v_cvt_pk_bf16_f32 v135, v130, v131
	s_nop 1
	v_permlane16_swap_b32_e32 v140, v142
	v_permlane16_swap_b32_e32 v141, v143
	v_permlane16_swap_b32_e32 v132, v134
	v_permlane16_swap_b32_e32 v133, v135
	global_store_dwordx4 v[184:185], v[140:143], off
	global_store_dwordx4 v[184:185], v[132:135], off offset:64
	s_and_b64 vcc, exec, s[6:7]
	s_cbranch_vccz .LBB0_180

; DI u32x2 pk4(f32x4 v) { u32x2 r; r.x = pk2(v[0], v[1]); r.y = pk2(v[2], v[3]); return r; }
;     DI void operator()(const AccT& acc, const Unit& u, int wr, int wc, int fr, int fq, LAS unsigned char*) const {
;     ...
;                 if (kind == 0 || kind == 3) {
;                     bf16_t* q = (bf16_t*)(ws + (kind == 0 ? WS_QA : WS_QB)) + ((size_t)h * MTOK + row) * 64 + 4 * fq;
; #pragma unroll
;                     for (int bj = 0; bj < 2; ++bj)
; #pragma unroll
;                         for (int n = 0; n < 2; ++n) *(u32x2*)(q + 32 * bj + 16 * n) = pk4(v[bj][n] * QSCALE);
.LBB0_506:
	s_and_b64 vcc, exec, s[0:1]
	s_cbranch_vccz .LBB0_229
	v_ashrrev_i32_e32 v129, 31, v128
	s_add_u32 s0, s36, s29
	v_lshl_add_u64 v[128:129], s[54:55], 0, v[128:129]
	s_addc_u32 s1, s37, 0
	v_lshlrev_b64 v[128:129], 7, v[128:129]
	v_lshl_add_u64 v[128:129], s[0:1], 0, v[128:129]
	v_lshlrev_b32_e32 v150, 1, v152
	v_pk_mul_f32 v[126:127], v[126:127], s[26:27] op_sel_hi:[1,0]
	v_pk_mul_f32 v[124:125], v[124:125], s[26:27] op_sel_hi:[1,0]
	v_pk_mul_f32 v[122:123], v[122:123], s[26:27] op_sel_hi:[1,0]
	v_pk_mul_f32 v[120:121], v[120:121], s[26:27] op_sel_hi:[1,0]
	v_pk_mul_f32 v[118:119], v[118:119], s[26:27] op_sel_hi:[1,0]
	v_pk_mul_f32 v[116:117], v[116:117], s[26:27] op_sel_hi:[1,0]
	v_pk_mul_f32 v[114:115], v[114:115], s[26:27] op_sel_hi:[1,0]
	v_pk_mul_f32 v[112:113], v[112:113], s[26:27] op_sel_hi:[1,0]
	v_lshl_add_u64 v[128:129], v[128:129], 0, v[150:151]
	v_and_b32_e32 v150, 8, v150
	v_mul_u32_u24_e32 v150, 3, v150
	v_lshl_add_u64 v[128:129], v[128:129], 0, v[150:151]
	v_cvt_pk_bf16_f32 v124, v124, v125
	v_cvt_pk_bf16_f32 v125, v126, v127
	v_cvt_pk_bf16_f32 v126, v120, v121
	v_cvt_pk_bf16_f32 v127, v122, v123
	v_cvt_pk_bf16_f32 v116, v116, v117
	v_cvt_pk_bf16_f32 v117, v118, v119
	v_cvt_pk_bf16_f32 v118, v112, v113
	v_cvt_pk_bf16_f32 v119, v114, v115
	s_nop 1
	v_permlane16_swap_b32_e32 v124, v126
	v_permlane16_swap_b32_e32 v125, v127
	v_permlane16_swap_b32_e32 v116, v118
	v_permlane16_swap_b32_e32 v117, v119
	global_store_dwordx4 v[128:129], v[124:127], off
	global_store_dwordx4 v[128:129], v[116:119], off offset:64
	s_and_b64 vcc, exec, s[6:7]
	s_cbranch_vccz .LBB0_230

; DI u32x2 pk4(f32x4 v) { u32x2 r; r.x = pk2(v[0], v[1]); r.y = pk2(v[2], v[3]); return r; }
;     DI void operator()(const AccT& acc, const Unit& u, int wr, int wc, int fr, int fq, LAS unsigned char*) const {
;     ...
;                 if (kind == 0 || kind == 3) {
;                     bf16_t* q = (bf16_t*)(ws + (kind == 0 ? WS_QA : WS_QB)) + ((size_t)h * MTOK + row) * 64 + 4 * fq;
; #pragma unroll
;                     for (int bj = 0; bj < 2; ++bj)
; #pragma unroll
;                         for (int n = 0; n < 2; ++n) *(u32x2*)(q + 32 * bj + 16 * n) = pk4(v[bj][n] * QSCALE);
.LBB0_510:
	s_and_b64 vcc, exec, s[0:1]
	s_cbranch_vccz .LBB0_275
	v_ashrrev_i32_e32 v113, 31, v112
	s_add_u32 s0, s36, s29
	v_lshl_add_u64 v[112:113], s[54:55], 0, v[112:113]
	s_addc_u32 s1, s37, 0
	v_lshlrev_b64 v[112:113], 7, v[112:113]
	v_lshl_add_u64 v[112:113], s[0:1], 0, v[112:113]
	v_lshlrev_b32_e32 v150, 1, v152
	v_pk_mul_f32 v[110:111], v[110:111], s[26:27] op_sel_hi:[1,0]
	v_pk_mul_f32 v[108:109], v[108:109], s[26:27] op_sel_hi:[1,0]
	v_pk_mul_f32 v[106:107], v[106:107], s[26:27] op_sel_hi:[1,0]
	v_pk_mul_f32 v[104:105], v[104:105], s[26:27] op_sel_hi:[1,0]
	v_pk_mul_f32 v[102:103], v[102:103], s[26:27] op_sel_hi:[1,0]
	v_pk_mul_f32 v[100:101], v[100:101], s[26:27] op_sel_hi:[1,0]
	v_pk_mul_f32 v[98:99], v[98:99], s[26:27] op_sel_hi:[1,0]
	v_pk_mul_f32 v[96:97], v[96:97], s[26:27] op_sel_hi:[1,0]
	v_lshl_add_u64 v[112:113], v[112:113], 0, v[150:151]
	v_and_b32_e32 v150, 8, v150
	v_mul_u32_u24_e32 v150, 3, v150
	v_lshl_add_u64 v[112:113], v[112:113], 0, v[150:151]
	v_cvt_pk_bf16_f32 v108, v108, v109
	v_cvt_pk_bf16_f32 v109, v110, v111
	v_cvt_pk_bf16_f32 v110, v104, v105
	v_cvt_pk_bf16_f32 v111, v106, v107
	v_cvt_pk_bf16_f32 v100, v100, v101
	v_cvt_pk_bf16_f32 v101, v102, v103
	v_cvt_pk_bf16_f32 v102, v96, v97
	v_cvt_pk_bf16_f32 v103, v98, v99
	s_nop 1
	v_permlane16_swap_b32_e32 v108, v110
	v_permlane16_swap_b32_e32 v109, v111
	v_permlane16_swap_b32_e32 v100, v102
	v_permlane16_swap_b32_e32 v101, v103
	global_store_dwordx4 v[112:113], v[108:111], off
	global_store_dwordx4 v[112:113], v[100:103], off offset:64
	s_and_b64 vcc, exec, s[6:7]
	s_cbranch_vccz .LBB0_276

; DI u32x2 pk4(f32x4 v) { u32x2 r; r.x = pk2(v[0], v[1]); r.y = pk2(v[2], v[3]); return r; }
;     DI void operator()(const AccT& acc, const Unit& u, int wr, int wc, int fr, int fq, LAS unsigned char*) const {
;     ...
;                 if (kind == 0 || kind == 3) {
;                     bf16_t* q = (bf16_t*)(ws + (kind == 0 ? WS_QA : WS_QB)) + ((size_t)h * MTOK + row) * 64 + 4 * fq;
; #pragma unroll
;                     for (int bj = 0; bj < 2; ++bj)
; #pragma unroll
;                         for (int n = 0; n < 2; ++n) *(u32x2*)(q + 32 * bj + 16 * n) = pk4(v[bj][n] * QSCALE);
.LBB0_514:
	s_and_b64 vcc, exec, s[0:1]
	s_cbranch_vccz .LBB0_321
	v_ashrrev_i32_e32 v97, 31, v96
	s_add_u32 s0, s36, s29
	v_lshl_add_u64 v[96:97], s[54:55], 0, v[96:97]
	s_addc_u32 s1, s37, 0
	v_lshlrev_b64 v[96:97], 7, v[96:97]
	v_lshl_add_u64 v[96:97], s[0:1], 0, v[96:97]
	v_lshlrev_b32_e32 v150, 1, v152
	v_pk_mul_f32 v[94:95], v[94:95], s[26:27] op_sel_hi:[1,0]
	v_pk_mul_f32 v[92:93], v[92:93], s[26:27] op_sel_hi:[1,0]
	v_pk_mul_f32 v[90:91], v[90:91], s[26:27] op_sel_hi:[1,0]
	v_pk_mul_f32 v[88:89], v[88:89], s[26:27] op_sel_hi:[1,0]
	v_pk_mul_f32 v[86:87], v[86:87], s[26:27] op_sel_hi:[1,0]
	v_pk_mul_f32 v[84:85], v[84:85], s[26:27] op_sel_hi:[1,0]
	v_pk_mul_f32 v[82:83], v[82:83], s[26:27] op_sel_hi:[1,0]
	v_pk_mul_f32 v[80:81], v[80:81], s[26:27] op_sel_hi:[1,0]
	v_lshl_add_u64 v[96:97], v[96:97], 0, v[150:151]
	v_and_b32_e32 v150, 8, v150
	v_mul_u32_u24_e32 v150, 3, v150
	v_lshl_add_u64 v[96:97], v[96:97], 0, v[150:151]
	v_cvt_pk_bf16_f32 v92, v92, v93
	v_cvt_pk_bf16_f32 v93, v94, v95
	v_cvt_pk_bf16_f32 v94, v88, v89
	v_cvt_pk_bf16_f32 v95, v90, v91
	v_cvt_pk_bf16_f32 v84, v84, v85
	v_cvt_pk_bf16_f32 v85, v86, v87
	v_cvt_pk_bf16_f32 v86, v80, v81
	v_cvt_pk_bf16_f32 v87, v82, v83
	s_nop 1
	v_permlane16_swap_b32_e32 v92, v94
	v_permlane16_swap_b32_e32 v93, v95
	v_permlane16_swap_b32_e32 v84, v86
	v_permlane16_swap_b32_e32 v85, v87
	global_store_dwordx4 v[96:97], v[92:95], off
	global_store_dwordx4 v[96:97], v[84:87], off offset:64
	s_and_b64 vcc, exec, s[6:7]
	s_cbranch_vccz .LBB0_322

; DI u32x2 pk4(f32x4 v) { u32x2 r; r.x = pk2(v[0], v[1]); r.y = pk2(v[2], v[3]); return r; }
;     DI void operator()(const AccT& acc, const Unit& u, int wr, int wc, int fr, int fq, LAS unsigned char*) const {
;     ...
;                 if (kind == 0 || kind == 3) {
;                     bf16_t* q = (bf16_t*)(ws + (kind == 0 ? WS_QA : WS_QB)) + ((size_t)h * MTOK + row) * 64 + 4 * fq;
; #pragma unroll
;                     for (int bj = 0; bj < 2; ++bj)
; #pragma unroll
;                         for (int n = 0; n < 2; ++n) *(u32x2*)(q + 32 * bj + 16 * n) = pk4(v[bj][n] * QSCALE);
.LBB0_518:
	s_and_b64 vcc, exec, s[0:1]
	s_cbranch_vccz .LBB0_367
	v_ashrrev_i32_e32 v81, 31, v80
	s_add_u32 s0, s36, s29
	v_lshl_add_u64 v[80:81], s[54:55], 0, v[80:81]
	s_addc_u32 s1, s37, 0
	v_lshlrev_b64 v[80:81], 7, v[80:81]
	v_lshl_add_u64 v[80:81], s[0:1], 0, v[80:81]
	v_lshlrev_b32_e32 v150, 1, v152
	v_pk_mul_f32 v[78:79], v[78:79], s[26:27] op_sel_hi:[1,0]
	v_pk_mul_f32 v[76:77], v[76:77], s[26:27] op_sel_hi:[1,0]
	v_pk_mul_f32 v[74:75], v[74:75], s[26:27] op_sel_hi:[1,0]
	v_pk_mul_f32 v[72:73], v[72:73], s[26:27] op_sel_hi:[1,0]
	v_pk_mul_f32 v[70:71], v[70:71], s[26:27] op_sel_hi:[1,0]
	v_pk_mul_f32 v[68:69], v[68:69], s[26:27] op_sel_hi:[1,0]
	v_pk_mul_f32 v[66:67], v[66:67], s[26:27] op_sel_hi:[1,0]
	v_pk_mul_f32 v[64:65], v[64:65], s[26:27] op_sel_hi:[1,0]
	v_lshl_add_u64 v[80:81], v[80:81], 0, v[150:151]
	v_and_b32_e32 v150, 8, v150
	v_mul_u32_u24_e32 v150, 3, v150
	v_lshl_add_u64 v[80:81], v[80:81], 0, v[150:151]
	v_cvt_pk_bf16_f32 v76, v76, v77
	v_cvt_pk_bf16_f32 v77, v78, v79
	v_cvt_pk_bf16_f32 v78, v72, v73
	v_cvt_pk_bf16_f32 v79, v74, v75
	v_cvt_pk_bf16_f32 v68, v68, v69
	v_cvt_pk_bf16_f32 v69, v70, v71
	v_cvt_pk_bf16_f32 v70, v64, v65
	v_cvt_pk_bf16_f32 v71, v66, v67
	s_nop 1
	v_permlane16_swap_b32_e32 v76, v78
	v_permlane16_swap_b32_e32 v77, v79
	v_permlane16_swap_b32_e32 v68, v70
	v_permlane16_swap_b32_e32 v69, v71
	global_store_dwordx4 v[80:81], v[76:79], off
	global_store_dwordx4 v[80:81], v[68:71], off offset:64
	s_and_b64 vcc, exec, s[6:7]
	s_cbranch_vccz .LBB0_368

; DI u32x2 pk4(f32x4 v) { u32x2 r; r.x = pk2(v[0], v[1]); r.y = pk2(v[2], v[3]); return r; }
;     DI void operator()(const AccT& acc, const Unit& u, int wr, int wc, int fr, int fq, LAS unsigned char*) const {
;     ...
;                 if (kind == 0 || kind == 3) {
;                     bf16_t* q = (bf16_t*)(ws + (kind == 0 ? WS_QA : WS_QB)) + ((size_t)h * MTOK + row) * 64 + 4 * fq;
; #pragma unroll
;                     for (int bj = 0; bj < 2; ++bj)
; #pragma unroll
;                         for (int n = 0; n < 2; ++n) *(u32x2*)(q + 32 * bj + 16 * n) = pk4(v[bj][n] * QSCALE);
.LBB0_522:
	s_and_b64 vcc, exec, s[0:1]
	s_cbranch_vccz .LBB0_413
	v_ashrrev_i32_e32 v65, 31, v64
	s_add_u32 s0, s36, s29
	v_lshl_add_u64 v[64:65], s[54:55], 0, v[64:65]
	s_addc_u32 s1, s37, 0
	v_lshlrev_b64 v[64:65], 7, v[64:65]
	v_lshl_add_u64 v[64:65], s[0:1], 0, v[64:65]
	v_lshlrev_b32_e32 v150, 1, v152
	v_pk_mul_f32 v[46:47], v[46:47], s[26:27] op_sel_hi:[1,0]
	v_pk_mul_f32 v[44:45], v[44:45], s[26:27] op_sel_hi:[1,0]
	v_pk_mul_f32 v[42:43], v[42:43], s[26:27] op_sel_hi:[1,0]
	v_pk_mul_f32 v[40:41], v[40:41], s[26:27] op_sel_hi:[1,0]
	v_pk_mul_f32 v[38:39], v[38:39], s[26:27] op_sel_hi:[1,0]
	v_pk_mul_f32 v[36:37], v[36:37], s[26:27] op_sel_hi:[1,0]
	v_pk_mul_f32 v[34:35], v[34:35], s[26:27] op_sel_hi:[1,0]
	v_pk_mul_f32 v[32:33], v[32:33], s[26:27] op_sel_hi:[1,0]
	v_lshl_add_u64 v[64:65], v[64:65], 0, v[150:151]
	v_and_b32_e32 v150, 8, v150
	v_mul_u32_u24_e32 v150, 3, v150
	v_lshl_add_u64 v[64:65], v[64:65], 0, v[150:151]
	v_cvt_pk_bf16_f32 v44, v44, v45
	v_cvt_pk_bf16_f32 v45, v46, v47
	v_cvt_pk_bf16_f32 v46, v40, v41
	v_cvt_pk_bf16_f32 v47, v42, v43
	v_cvt_pk_bf16_f32 v36, v36, v37
	v_cvt_pk_bf16_f32 v37, v38, v39
	v_cvt_pk_bf16_f32 v38, v32, v33
	v_cvt_pk_bf16_f32 v39, v34, v35
	s_nop 1
	v_permlane16_swap_b32_e32 v44, v46
	v_permlane16_swap_b32_e32 v45, v47
	v_permlane16_swap_b32_e32 v36, v38
	v_permlane16_swap_b32_e32 v37, v39
	global_store_dwordx4 v[64:65], v[44:47], off
	global_store_dwordx4 v[64:65], v[36:39], off offset:64
	s_and_b64 vcc, exec, s[6:7]
	s_cbranch_vccz .LBB0_414

; DI u32x2 pk4(f32x4 v) { u32x2 r; r.x = pk2(v[0], v[1]); r.y = pk2(v[2], v[3]); return r; }
;     DI void operator()(const AccT& acc, const Unit& u, int wr, int wc, int fr, int fq, LAS unsigned char*) const {
;     ...
;                 if (kind == 0 || kind == 3) {
;                     bf16_t* q = (bf16_t*)(ws + (kind == 0 ? WS_QA : WS_QB)) + ((size_t)h * MTOK + row) * 64 + 4 * fq;
; #pragma unroll
;                     for (int bj = 0; bj < 2; ++bj)
; #pragma unroll
;                         for (int n = 0; n < 2; ++n) *(u32x2*)(q + 32 * bj + 16 * n) = pk4(v[bj][n] * QSCALE);
.LBB0_526:
	s_and_b64 vcc, exec, s[0:1]
	s_cbranch_vccz .LBB0_459
	v_ashrrev_i32_e32 v33, 31, v32
	s_add_u32 s0, s36, s29
	v_lshl_add_u64 v[32:33], s[54:55], 0, v[32:33]
	s_addc_u32 s1, s37, 0
	v_lshlrev_b64 v[32:33], 7, v[32:33]
	v_lshl_add_u64 v[32:33], s[0:1], 0, v[32:33]
	v_lshlrev_b32_e32 v150, 1, v152
	v_pk_mul_f32 v[30:31], v[30:31], s[26:27] op_sel_hi:[1,0]
	v_pk_mul_f32 v[28:29], v[28:29], s[26:27] op_sel_hi:[1,0]
	v_pk_mul_f32 v[26:27], v[26:27], s[26:27] op_sel_hi:[1,0]
	v_pk_mul_f32 v[24:25], v[24:25], s[26:27] op_sel_hi:[1,0]
	v_pk_mul_f32 v[22:23], v[22:23], s[26:27] op_sel_hi:[1,0]
	v_pk_mul_f32 v[20:21], v[20:21], s[26:27] op_sel_hi:[1,0]
	v_pk_mul_f32 v[18:19], v[18:19], s[26:27] op_sel_hi:[1,0]
	v_pk_mul_f32 v[16:17], v[16:17], s[26:27] op_sel_hi:[1,0]
	v_lshl_add_u64 v[32:33], v[32:33], 0, v[150:151]
	v_and_b32_e32 v150, 8, v150
	v_mul_u32_u24_e32 v150, 3, v150
	v_lshl_add_u64 v[32:33], v[32:33], 0, v[150:151]
	v_cvt_pk_bf16_f32 v28, v28, v29
	v_cvt_pk_bf16_f32 v29, v30, v31
	v_cvt_pk_bf16_f32 v30, v24, v25
	v_cvt_pk_bf16_f32 v31, v26, v27
	v_cvt_pk_bf16_f32 v20, v20, v21
	v_cvt_pk_bf16_f32 v21, v22, v23
	v_cvt_pk_bf16_f32 v22, v16, v17
	v_cvt_pk_bf16_f32 v23, v18, v19
	s_nop 1
	v_permlane16_swap_b32_e32 v28, v30
	v_permlane16_swap_b32_e32 v29, v31
	v_permlane16_swap_b32_e32 v20, v22
	v_permlane16_swap_b32_e32 v21, v23
	global_store_dwordx4 v[32:33], v[28:31], off
	global_store_dwordx4 v[32:33], v[20:23], off offset:64
	s_and_b64 vcc, exec, s[6:7]
	s_cbranch_vccz .LBB0_460

; DI u32x2 pk4(f32x4 v) { u32x2 r; r.x = pk2(v[0], v[1]); r.y = pk2(v[2], v[3]); return r; }
;     DI void operator()(const AccT& acc, const Unit& u, int wr, int wc, int fr, int fq, LAS unsigned char*) const {
;     ...
;                 if (kind == 0 || kind == 3) {
;                     bf16_t* q = (bf16_t*)(ws + (kind == 0 ? WS_QA : WS_QB)) + ((size_t)h * MTOK + row) * 64 + 4 * fq;
; #pragma unroll
;                     for (int bj = 0; bj < 2; ++bj)
; #pragma unroll
;                         for (int n = 0; n < 2; ++n) *(u32x2*)(q + 32 * bj + 16 * n) = pk4(v[bj][n] * QSCALE);
.LBB0_530:
	s_and_b64 vcc, exec, s[0:1]
	s_cbranch_vccz .LBB0_505
	v_ashrrev_i32_e32 v17, 31, v16
	s_add_u32 s0, s36, s29
	v_lshl_add_u64 v[16:17], s[54:55], 0, v[16:17]
	s_addc_u32 s1, s37, 0
	v_lshlrev_b64 v[16:17], 7, v[16:17]
	v_lshl_add_u64 v[16:17], s[0:1], 0, v[16:17]
	v_lshlrev_b32_e32 v150, 1, v152
	v_pk_mul_f32 v[14:15], v[14:15], s[26:27] op_sel_hi:[1,0]
	v_pk_mul_f32 v[12:13], v[12:13], s[26:27] op_sel_hi:[1,0]
	v_pk_mul_f32 v[10:11], v[10:11], s[26:27] op_sel_hi:[1,0]
	v_pk_mul_f32 v[8:9], v[8:9], s[26:27] op_sel_hi:[1,0]
	v_pk_mul_f32 v[6:7], v[6:7], s[26:27] op_sel_hi:[1,0]
	v_pk_mul_f32 v[4:5], v[4:5], s[26:27] op_sel_hi:[1,0]
	v_pk_mul_f32 v[2:3], v[2:3], s[26:27] op_sel_hi:[1,0]
	v_pk_mul_f32 v[0:1], v[0:1], s[26:27] op_sel_hi:[1,0]
	v_lshl_add_u64 v[16:17], v[16:17], 0, v[150:151]
	v_and_b32_e32 v150, 8, v150
	v_mul_u32_u24_e32 v150, 3, v150
	v_lshl_add_u64 v[16:17], v[16:17], 0, v[150:151]
	v_cvt_pk_bf16_f32 v12, v12, v13
	v_cvt_pk_bf16_f32 v13, v14, v15
	v_cvt_pk_bf16_f32 v14, v8, v9
	v_cvt_pk_bf16_f32 v15, v10, v11
	v_cvt_pk_bf16_f32 v4, v4, v5
	v_cvt_pk_bf16_f32 v5, v6, v7
	v_cvt_pk_bf16_f32 v6, v0, v1
	v_cvt_pk_bf16_f32 v7, v2, v3
	s_nop 1
	v_permlane16_swap_b32_e32 v12, v14
	v_permlane16_swap_b32_e32 v13, v15
	v_permlane16_swap_b32_e32 v4, v6
	v_permlane16_swap_b32_e32 v5, v7
	global_store_dwordx4 v[16:17], v[12:15], off
	global_store_dwordx4 v[16:17], v[4:7], off offset:64
	s_andn2_b64 vcc, exec, s[4:5]
	s_mov_b64 s[0:1], -1
	s_cbranch_vccnz .LBB0_100
